# b17 + INB (EpiMulB): second-half scales and six operand loads hoisted above first-half math/stores
# baseline (speedup 1.0000x reference)
.LBB0_286:
	ds_read_b128 v[128:131], v162
	ds_read_b128 v[148:151], v162 offset:1024
	ds_read_b128 v[152:155], v162 offset:2048
	ds_read_b128 v[166:169], v162 offset:3072
	s_add_u32 s36, s34, 0xfffc0080
	s_addc_u32 s37, s35, -1
	s_cmp_eq_u32 s59, 12
	s_cselect_b32 s39, s23, s37
	s_cselect_b32 s38, s55, s36
	s_cselect_b32 s37, s21, s58
	s_cselect_b32 s36, s56, s57
	v_lshl_add_u64 v[156:157], s[34:35], 0, v[140:141]
	s_add_i32 m0, s31, 0xc000
	ds_read_b128 v[170:173], v163
	ds_read_b128 v[174:177], v163 offset:1024
	ds_read_b128 v[178:181], v163 offset:2048
	ds_read_b128 v[182:185], v163 offset:3072
	ds_read_b128 v[190:193], v163 offset:4096
	ds_read_b128 v[194:197], v163 offset:5120
	ds_read_b128 v[198:201], v163 offset:6144
	ds_read_b128 v[202:205], v163 offset:7168
	global_load_lds_dwordx4 v[156:157], off
	v_lshl_add_u64 v[156:157], s[34:35], 0, v[142:143]
	s_add_i32 m0, s31, 0xe000
	s_nop 0
	global_load_lds_dwordx4 v[156:157], off
	s_waitcnt lgkmcnt(8)
	s_barrier
	s_waitcnt lgkmcnt(0)
	s_setprio 1
	s_waitcnt lgkmcnt(0)
	v_mfma_f32_16x16x32_bf16 v[124:127], v[128:131], v[170:173], v[124:127]
	v_mfma_f32_16x16x32_bf16 v[120:123], v[152:155], v[170:173], v[120:123]
	v_mfma_f32_16x16x32_bf16 v[108:111], v[128:131], v[178:181], v[108:111]
	v_mfma_f32_16x16x32_bf16 v[104:107], v[152:155], v[178:181], v[104:107]
	v_mfma_f32_16x16x32_bf16 v[92:95], v[128:131], v[190:193], v[92:95]
	v_mfma_f32_16x16x32_bf16 v[88:91], v[152:155], v[190:193], v[88:91]
	v_mfma_f32_16x16x32_bf16 v[76:79], v[128:131], v[198:201], v[76:79]
	v_mfma_f32_16x16x32_bf16 v[72:75], v[152:155], v[198:201], v[72:75]
	v_mfma_f32_16x16x32_bf16 v[124:127], v[148:151], v[174:177], v[124:127]
	v_mfma_f32_16x16x32_bf16 v[120:123], v[166:169], v[174:177], v[120:123]
	v_mfma_f32_16x16x32_bf16 v[108:111], v[148:151], v[182:185], v[108:111]
	v_mfma_f32_16x16x32_bf16 v[104:107], v[166:169], v[182:185], v[104:107]
	v_mfma_f32_16x16x32_bf16 v[92:95], v[148:151], v[194:197], v[92:95]
	v_mfma_f32_16x16x32_bf16 v[88:91], v[166:169], v[194:197], v[88:91]
	v_mfma_f32_16x16x32_bf16 v[76:79], v[148:151], v[202:205], v[76:79]
	v_mfma_f32_16x16x32_bf16 v[72:75], v[166:169], v[202:205], v[72:75]
	s_setprio 0
	s_barrier
	s_add_i32 s60, s52, s44
	v_lshl_add_u64 v[156:157], s[36:37], 0, v[134:135]
	s_mov_b32 m0, s60
	ds_read_b128 v[206:209], v164
	ds_read_b128 v[210:213], v164 offset:1024
	ds_read_b128 v[214:217], v164 offset:2048
	ds_read_b128 v[218:221], v164 offset:3072
	global_load_lds_dwordx4 v[156:157], off
	v_lshl_add_u64 v[186:187], s[36:37], 0, v[138:139]
	s_add_i32 m0, s60, 0x2000
	s_nop 0
	global_load_lds_dwordx4 v[186:187], off
	s_barrier
	s_waitcnt lgkmcnt(0)
	s_setprio 1
	s_waitcnt lgkmcnt(0)
	v_mfma_f32_16x16x32_bf16 v[116:119], v[206:209], v[170:173], v[116:119]
	v_mfma_f32_16x16x32_bf16 v[112:115], v[214:217], v[170:173], v[112:115]
	v_mfma_f32_16x16x32_bf16 v[100:103], v[206:209], v[178:181], v[100:103]
	v_mfma_f32_16x16x32_bf16 v[96:99], v[214:217], v[178:181], v[96:99]
	v_mfma_f32_16x16x32_bf16 v[84:87], v[206:209], v[190:193], v[84:87]
	v_mfma_f32_16x16x32_bf16 v[80:83], v[214:217], v[190:193], v[80:83]
	v_mfma_f32_16x16x32_bf16 v[68:71], v[206:209], v[198:201], v[68:71]
	v_mfma_f32_16x16x32_bf16 v[64:67], v[214:217], v[198:201], v[64:67]
	v_mfma_f32_16x16x32_bf16 v[116:119], v[210:213], v[174:177], v[116:119]
	v_mfma_f32_16x16x32_bf16 v[112:115], v[218:221], v[174:177], v[112:115]
	v_mfma_f32_16x16x32_bf16 v[100:103], v[210:213], v[182:185], v[100:103]
	v_mfma_f32_16x16x32_bf16 v[96:99], v[218:221], v[182:185], v[96:99]
	v_mfma_f32_16x16x32_bf16 v[84:87], v[210:213], v[194:197], v[84:87]
	v_mfma_f32_16x16x32_bf16 v[80:83], v[218:221], v[194:197], v[80:83]
	v_mfma_f32_16x16x32_bf16 v[68:71], v[210:213], v[202:205], v[68:71]
	v_mfma_f32_16x16x32_bf16 v[64:67], v[218:221], v[202:205], v[64:67]
	s_setprio 0
	s_mov_b32 m0, s31
	v_lshl_add_u64 v[222:223], s[38:39], 0, v[132:133]
	s_barrier
	ds_read_b128 v[170:173], v163 offset:16384
	ds_read_b128 v[174:177], v163 offset:17408
	ds_read_b128 v[178:181], v163 offset:18432
	ds_read_b128 v[182:185], v163 offset:19456
	ds_read_b128 v[190:193], v163 offset:20480
	ds_read_b128 v[194:197], v163 offset:21504
	ds_read_b128 v[198:201], v163 offset:22528
	ds_read_b128 v[202:205], v163 offset:23552
	global_load_lds_dwordx4 v[222:223], off
	v_lshl_add_u64 v[224:225], s[38:39], 0, v[136:137]
	s_mov_b32 m0, s45
	s_nop 0
	global_load_lds_dwordx4 v[224:225], off
	s_barrier
	s_waitcnt lgkmcnt(0)
	s_setprio 1
	s_waitcnt lgkmcnt(0)
	v_mfma_f32_16x16x32_bf16 v[60:63], v[128:131], v[170:173], v[60:63]
	v_mfma_f32_16x16x32_bf16 v[56:59], v[152:155], v[170:173], v[56:59]
	v_mfma_f32_16x16x32_bf16 v[44:47], v[128:131], v[178:181], v[44:47]
	v_mfma_f32_16x16x32_bf16 v[40:43], v[152:155], v[178:181], v[40:43]
	v_mfma_f32_16x16x32_bf16 v[28:31], v[128:131], v[190:193], v[28:31]
	v_mfma_f32_16x16x32_bf16 v[24:27], v[152:155], v[190:193], v[24:27]
	v_mfma_f32_16x16x32_bf16 v[12:15], v[128:131], v[198:201], v[12:15]
	v_mfma_f32_16x16x32_bf16 v[8:11], v[152:155], v[198:201], v[8:11]
	v_mfma_f32_16x16x32_bf16 v[60:63], v[148:151], v[174:177], v[60:63]
	v_mfma_f32_16x16x32_bf16 v[56:59], v[166:169], v[174:177], v[56:59]
	v_mfma_f32_16x16x32_bf16 v[44:47], v[148:151], v[182:185], v[44:47]
	v_mfma_f32_16x16x32_bf16 v[40:43], v[166:169], v[182:185], v[40:43]
	v_mfma_f32_16x16x32_bf16 v[28:31], v[148:151], v[194:197], v[28:31]
	v_mfma_f32_16x16x32_bf16 v[24:27], v[166:169], v[194:197], v[24:27]
	v_mfma_f32_16x16x32_bf16 v[12:15], v[148:151], v[202:205], v[12:15]
	v_mfma_f32_16x16x32_bf16 v[8:11], v[166:169], v[202:205], v[8:11]
	s_setprio 0
	s_barrier
	s_add_u32 s60, s36, 0x40000
	s_addc_u32 s61, s37, 0
	s_add_i32 s62, s53, s44
	v_lshl_add_u64 v[128:129], s[60:61], 0, v[134:135]
	s_mov_b32 m0, s62
	s_nop 0
	global_load_lds_dwordx4 v[128:129], off
	v_lshl_add_u64 v[128:129], s[60:61], 0, v[138:139]
	s_add_i32 m0, s62, 0x2000
	s_nop 0
	global_load_lds_dwordx4 v[128:129], off
	s_waitcnt vmcnt(6)
	s_barrier
	s_setprio 1
	v_mfma_f32_16x16x32_bf16 v[52:55], v[206:209], v[170:173], v[52:55]
	v_mfma_f32_16x16x32_bf16 v[48:51], v[214:217], v[170:173], v[48:51]
	v_mfma_f32_16x16x32_bf16 v[36:39], v[206:209], v[178:181], v[36:39]
	v_mfma_f32_16x16x32_bf16 v[32:35], v[214:217], v[178:181], v[32:35]
	v_mfma_f32_16x16x32_bf16 v[20:23], v[206:209], v[190:193], v[20:23]
	v_mfma_f32_16x16x32_bf16 v[16:19], v[214:217], v[190:193], v[16:19]
	v_mfma_f32_16x16x32_bf16 v[4:7], v[206:209], v[198:201], v[4:7]
	v_mfma_f32_16x16x32_bf16 v[0:3], v[214:217], v[198:201], v[0:3]
	v_mfma_f32_16x16x32_bf16 v[52:55], v[210:213], v[174:177], v[52:55]
	v_mfma_f32_16x16x32_bf16 v[48:51], v[218:221], v[174:177], v[48:51]
	v_mfma_f32_16x16x32_bf16 v[36:39], v[210:213], v[182:185], v[36:39]
	v_mfma_f32_16x16x32_bf16 v[32:35], v[218:221], v[182:185], v[32:35]
	v_mfma_f32_16x16x32_bf16 v[20:23], v[210:213], v[194:197], v[20:23]
	v_mfma_f32_16x16x32_bf16 v[16:19], v[218:221], v[194:197], v[16:19]
	v_mfma_f32_16x16x32_bf16 v[4:7], v[210:213], v[202:205], v[4:7]
	v_mfma_f32_16x16x32_bf16 v[0:3], v[218:221], v[202:205], v[0:3]
	s_setprio 0
	s_add_i32 s60, 0, 0x18000
	v_add_u32_e32 v158, s60, v160
	s_barrier
	ds_read_b128 v[128:131], v158
	ds_read_b128 v[148:151], v158 offset:1024
	ds_read_b128 v[152:155], v158 offset:2048
	ds_read_b128 v[166:169], v158 offset:3072
	s_add_u32 s38, s38, 0x40000
	s_addc_u32 s39, s39, 0
	s_mov_b32 m0, s46
	v_lshl_add_u64 v[206:207], s[38:39], 0, v[132:133]
	ds_read_b128 v[170:173], v163 offset:32768
	ds_read_b128 v[174:177], v163 offset:33792
	ds_read_b128 v[178:181], v163 offset:34816
	ds_read_b128 v[182:185], v163 offset:35840
	ds_read_b128 v[190:193], v163 offset:36864
	ds_read_b128 v[194:197], v163 offset:37888
	ds_read_b128 v[198:201], v163 offset:38912
	ds_read_b128 v[202:205], v163 offset:39936
	global_load_lds_dwordx4 v[206:207], off
	v_lshl_add_u64 v[206:207], s[38:39], 0, v[136:137]
	s_mov_b32 m0, s47
	s_nop 0
	global_load_lds_dwordx4 v[206:207], off
	s_waitcnt lgkmcnt(8)
	s_barrier
	s_waitcnt lgkmcnt(0)
	s_setprio 1
	s_waitcnt lgkmcnt(0)
	v_mfma_f32_16x16x32_bf16 v[124:127], v[128:131], v[170:173], v[124:127]
	v_mfma_f32_16x16x32_bf16 v[120:123], v[152:155], v[170:173], v[120:123]
	v_mfma_f32_16x16x32_bf16 v[108:111], v[128:131], v[178:181], v[108:111]
	v_mfma_f32_16x16x32_bf16 v[104:107], v[152:155], v[178:181], v[104:107]
	v_mfma_f32_16x16x32_bf16 v[92:95], v[128:131], v[190:193], v[92:95]
	v_mfma_f32_16x16x32_bf16 v[88:91], v[152:155], v[190:193], v[88:91]
	v_mfma_f32_16x16x32_bf16 v[76:79], v[128:131], v[198:201], v[76:79]
	v_mfma_f32_16x16x32_bf16 v[72:75], v[152:155], v[198:201], v[72:75]
	v_mfma_f32_16x16x32_bf16 v[124:127], v[148:151], v[174:177], v[124:127]
	v_mfma_f32_16x16x32_bf16 v[120:123], v[166:169], v[174:177], v[120:123]
	v_mfma_f32_16x16x32_bf16 v[108:111], v[148:151], v[182:185], v[108:111]
	v_mfma_f32_16x16x32_bf16 v[104:107], v[166:169], v[182:185], v[104:107]
	v_mfma_f32_16x16x32_bf16 v[92:95], v[148:151], v[194:197], v[92:95]
	v_mfma_f32_16x16x32_bf16 v[88:91], v[166:169], v[194:197], v[88:91]
	v_mfma_f32_16x16x32_bf16 v[76:79], v[148:151], v[202:205], v[76:79]
	v_mfma_f32_16x16x32_bf16 v[72:75], v[166:169], v[202:205], v[72:75]
	s_setprio 0
	s_barrier
	s_add_i32 s38, 0, 0x1c000
	s_add_i32 s39, s60, s44
	v_add_u32_e32 v158, s38, v160
	v_lshl_add_u64 v[156:157], v[156:157], 0, s[8:9]
	s_mov_b32 m0, s39
	ds_read_b128 v[206:209], v158
	ds_read_b128 v[210:213], v158 offset:1024
	ds_read_b128 v[214:217], v158 offset:2048
	ds_read_b128 v[218:221], v158 offset:3072
	global_load_lds_dwordx4 v[156:157], off
	v_lshl_add_u64 v[156:157], v[186:187], 0, s[8:9]
	s_add_i32 m0, s39, 0x2000
	s_nop 0
	global_load_lds_dwordx4 v[156:157], off
	s_barrier
	s_waitcnt lgkmcnt(0)
	s_setprio 1
	s_waitcnt lgkmcnt(0)
	v_mfma_f32_16x16x32_bf16 v[116:119], v[206:209], v[170:173], v[116:119]
	v_mfma_f32_16x16x32_bf16 v[112:115], v[214:217], v[170:173], v[112:115]
	v_mfma_f32_16x16x32_bf16 v[100:103], v[206:209], v[178:181], v[100:103]
	v_mfma_f32_16x16x32_bf16 v[96:99], v[214:217], v[178:181], v[96:99]
	v_mfma_f32_16x16x32_bf16 v[84:87], v[206:209], v[190:193], v[84:87]
	v_mfma_f32_16x16x32_bf16 v[80:83], v[214:217], v[190:193], v[80:83]
	v_mfma_f32_16x16x32_bf16 v[68:71], v[206:209], v[198:201], v[68:71]
	v_mfma_f32_16x16x32_bf16 v[64:67], v[214:217], v[198:201], v[64:67]
	v_mfma_f32_16x16x32_bf16 v[116:119], v[210:213], v[174:177], v[116:119]
	v_mfma_f32_16x16x32_bf16 v[112:115], v[218:221], v[174:177], v[112:115]
	v_mfma_f32_16x16x32_bf16 v[100:103], v[210:213], v[182:185], v[100:103]
	v_mfma_f32_16x16x32_bf16 v[96:99], v[218:221], v[182:185], v[96:99]
	v_mfma_f32_16x16x32_bf16 v[84:87], v[210:213], v[194:197], v[84:87]
	v_mfma_f32_16x16x32_bf16 v[80:83], v[218:221], v[194:197], v[80:83]
	v_mfma_f32_16x16x32_bf16 v[68:71], v[210:213], v[202:205], v[68:71]
	v_mfma_f32_16x16x32_bf16 v[64:67], v[218:221], v[202:205], v[64:67]
	s_setprio 0
	s_mov_b32 m0, s49
	v_lshl_add_u64 v[156:157], v[222:223], 0, s[8:9]
	s_barrier
	ds_read_b128 v[170:173], v163 offset:49152
	ds_read_b128 v[174:177], v163 offset:50176
	ds_read_b128 v[178:181], v163 offset:51200
	ds_read_b128 v[182:185], v163 offset:52224
	ds_read_b128 v[190:193], v163 offset:53248
	ds_read_b128 v[194:197], v163 offset:54272
	ds_read_b128 v[198:201], v163 offset:55296
	ds_read_b128 v[202:205], v163 offset:56320
	global_load_lds_dwordx4 v[156:157], off
	v_lshl_add_u64 v[156:157], v[224:225], 0, s[8:9]
	s_mov_b32 m0, s50
	s_nop 0
	global_load_lds_dwordx4 v[156:157], off
	s_barrier
	s_waitcnt lgkmcnt(0)
	s_setprio 1
	s_waitcnt lgkmcnt(0)
	v_mfma_f32_16x16x32_bf16 v[60:63], v[128:131], v[170:173], v[60:63]
	v_mfma_f32_16x16x32_bf16 v[56:59], v[152:155], v[170:173], v[56:59]
	v_mfma_f32_16x16x32_bf16 v[44:47], v[128:131], v[178:181], v[44:47]
	v_mfma_f32_16x16x32_bf16 v[40:43], v[152:155], v[178:181], v[40:43]
	v_mfma_f32_16x16x32_bf16 v[28:31], v[128:131], v[190:193], v[28:31]
	v_mfma_f32_16x16x32_bf16 v[24:27], v[152:155], v[190:193], v[24:27]
	v_mfma_f32_16x16x32_bf16 v[12:15], v[128:131], v[198:201], v[12:15]
	v_mfma_f32_16x16x32_bf16 v[8:11], v[152:155], v[198:201], v[8:11]
	v_mfma_f32_16x16x32_bf16 v[60:63], v[148:151], v[174:177], v[60:63]
	v_mfma_f32_16x16x32_bf16 v[56:59], v[166:169], v[174:177], v[56:59]
	v_mfma_f32_16x16x32_bf16 v[44:47], v[148:151], v[182:185], v[44:47]
	v_mfma_f32_16x16x32_bf16 v[40:43], v[166:169], v[182:185], v[40:43]
	v_mfma_f32_16x16x32_bf16 v[28:31], v[148:151], v[194:197], v[28:31]
	v_mfma_f32_16x16x32_bf16 v[24:27], v[166:169], v[194:197], v[24:27]
	v_mfma_f32_16x16x32_bf16 v[12:15], v[148:151], v[202:205], v[12:15]
	v_mfma_f32_16x16x32_bf16 v[8:11], v[166:169], v[202:205], v[8:11]
	s_setprio 0
	s_barrier
	s_add_u32 s36, s36, 0x40080
	s_addc_u32 s37, s37, 0
	s_add_i32 s38, s38, s44
	v_lshl_add_u64 v[128:129], s[36:37], 0, v[134:135]
	s_mov_b32 m0, s38
	s_nop 0
	global_load_lds_dwordx4 v[128:129], off
	v_lshl_add_u64 v[128:129], s[36:37], 0, v[138:139]
	s_add_i32 m0, s38, 0x2000
	s_nop 0
	global_load_lds_dwordx4 v[128:129], off
	s_waitcnt vmcnt(6)
	s_barrier
	s_setprio 1
	v_mfma_f32_16x16x32_bf16 v[52:55], v[206:209], v[170:173], v[52:55]
	v_mfma_f32_16x16x32_bf16 v[48:51], v[214:217], v[170:173], v[48:51]
	v_mfma_f32_16x16x32_bf16 v[36:39], v[206:209], v[178:181], v[36:39]
	v_mfma_f32_16x16x32_bf16 v[32:35], v[214:217], v[178:181], v[32:35]
	v_mfma_f32_16x16x32_bf16 v[20:23], v[206:209], v[190:193], v[20:23]
	v_mfma_f32_16x16x32_bf16 v[16:19], v[214:217], v[190:193], v[16:19]
	v_mfma_f32_16x16x32_bf16 v[4:7], v[206:209], v[198:201], v[4:7]
	v_mfma_f32_16x16x32_bf16 v[0:3], v[214:217], v[198:201], v[0:3]
	v_mfma_f32_16x16x32_bf16 v[52:55], v[210:213], v[174:177], v[52:55]
	v_mfma_f32_16x16x32_bf16 v[48:51], v[218:221], v[174:177], v[48:51]
	v_mfma_f32_16x16x32_bf16 v[36:39], v[210:213], v[182:185], v[36:39]
	v_mfma_f32_16x16x32_bf16 v[32:35], v[218:221], v[182:185], v[32:35]
	v_mfma_f32_16x16x32_bf16 v[20:23], v[210:213], v[194:197], v[20:23]
	v_mfma_f32_16x16x32_bf16 v[16:19], v[218:221], v[194:197], v[16:19]
	v_mfma_f32_16x16x32_bf16 v[4:7], v[210:213], v[202:205], v[4:7]
	v_mfma_f32_16x16x32_bf16 v[0:3], v[218:221], v[202:205], v[0:3]
	s_setprio 0
	s_add_i32 s59, s59, 2
	s_add_u32 s34, s34, 0x100
	s_addc_u32 s35, s35, 0
	s_add_u32 s57, s57, 0x100
	s_addc_u32 s58, s58, 0
	s_cmp_gt_u32 s59, 13
	s_barrier
	s_cbranch_scc0 .LBB0_286
	v_lshl_add_u32 v128, s30, 8, v159
	v_or_b32_e32 v156, 16, v128
	v_lshl_or_b32 v130, s54, 8, v161
	v_ashrrev_i32_e32 v129, 31, v128
	v_ashrrev_i32_e32 v157, 31, v156
	v_ashrrev_i32_e32 v131, 31, v130
	v_lshl_add_u64 v[152:153], v[128:129], 2, s[10:11]
	v_lshlrev_b64 v[154:155], 11, v[128:129]
	v_lshl_add_u64 v[170:171], v[156:157], 2, s[10:11]
	v_lshlrev_b64 v[186:187], 11, v[156:157]
	v_or_b32_e32 v156, 32, v128
	v_or_b32_e32 v128, 48, v128
	v_lshlrev_b64 v[148:149], 1, v[130:131]
	v_ashrrev_i32_e32 v157, 31, v156
	v_ashrrev_i32_e32 v129, 31, v128
	v_lshl_add_u64 v[150:151], s[0:1], 0, v[148:149]
	v_lshl_add_u64 v[182:183], v[156:157], 2, s[10:11]
	v_lshlrev_b64 v[198:199], 11, v[156:157]
	v_lshlrev_b64 v[156:157], 11, v[128:129]
	v_lshl_add_u64 v[130:131], v[150:151], 0, v[154:155]
	v_lshl_add_u64 v[178:179], v[150:151], 0, v[186:187]
	v_lshl_add_u64 v[190:191], v[150:151], 0, v[198:199]
	v_lshl_add_u64 v[192:193], v[128:129], 2, s[10:11]
	v_lshl_add_u64 v[128:129], v[150:151], 0, v[156:157]
	global_load_dword v200, v[152:153], off
	global_load_dwordx4 v[166:169], v[130:131], off
	global_load_dword v202, v[170:171], off
	s_nop 0
	global_load_dwordx4 v[170:173], v[130:131], off offset:256
	global_load_dwordx4 v[174:177], v[178:179], off
	s_nop 0
	global_load_dwordx4 v[178:181], v[178:179], off offset:256
	s_nop 0
	global_load_dword v204, v[182:183], off
	s_nop 0
	global_load_dwordx4 v[182:185], v[190:191], off
	global_load_dword v158, v[192:193], off
	s_nop 0
	global_load_dwordx4 v[190:193], v[190:191], off offset:256
	s_nop 0
	global_load_dwordx4 v[194:197], v[128:129], off
	s_nop 0
	global_load_dwordx4 v[128:131], v[128:129], off offset:256
	global_load_dword v216, v[152:153], off offset:512
	global_load_dword v218, v[152:153], off offset:576
	global_load_dword v220, v[152:153], off offset:640
	v_lshl_add_u64 v[252:253], v[154:155], 0, s[6:7]
	v_lshl_add_u64 v[252:253], v[150:151], 0, v[252:253]
	global_load_dwordx4 v[236:239], v[252:253], off
	global_load_dwordx4 v[240:243], v[252:253], off offset:256
	v_lshl_add_u64 v[252:253], v[154:155], 0, s[12:13]
	v_lshl_add_u64 v[252:253], v[150:151], 0, v[252:253]
	global_load_dwordx4 v[244:247], v[252:253], off
	global_load_dwordx4 v[248:251], v[252:253], off offset:256
	v_lshl_add_u64 v[252:253], v[154:155], 0, s[14:15]
	v_lshl_add_u64 v[252:253], v[150:151], 0, v[252:253]
	global_load_dwordx4 v[208:211], v[252:253], off
	global_load_dwordx4 v[212:215], v[252:253], off offset:256
	global_load_dword v252, v[152:153], off offset:704
	s_waitcnt vmcnt(10)
	v_pk_mul_f32 v[124:125], v[124:125], v[200:201] op_sel_hi:[1,0]
	v_pk_mul_f32 v[206:207], v[122:123], v[200:201] op_sel_hi:[1,0]
	v_pk_mul_f32 v[122:123], v[120:121], v[200:201] op_sel_hi:[1,0]
	v_lshlrev_b32_e32 v120, 16, v166
	v_and_b32_e32 v121, 0xffff0000, v166
	v_mul_f32_e32 v120, v124, v120
	v_mul_f32_e32 v121, v125, v121
	v_pk_mul_f32 v[126:127], v[126:127], v[200:201] op_sel_hi:[1,0]
	v_cvt_pk_bf16_f32 v120, v120, v121
	v_lshlrev_b32_e32 v121, 16, v167
	v_and_b32_e32 v124, 0xffff0000, v167
	v_mul_f32_e32 v121, v126, v121
	v_mul_f32_e32 v124, v127, v124
	v_cvt_pk_bf16_f32 v121, v121, v124
	v_lshlrev_b32_e32 v124, 16, v168
	v_mul_f32_e32 v122, v122, v124
	v_and_b32_e32 v124, 0xffff0000, v168
	v_mul_f32_e32 v123, v123, v124
	v_cvt_pk_bf16_f32 v122, v122, v123
	v_lshlrev_b32_e32 v123, 16, v169
	v_and_b32_e32 v124, 0xffff0000, v169
	v_mul_f32_e32 v123, v206, v123
	v_mul_f32_e32 v124, v207, v124
	v_cvt_pk_bf16_f32 v123, v123, v124
	v_lshl_add_u64 v[124:125], s[26:27], 0, v[154:155]
	v_lshl_add_u64 v[124:125], v[124:125], 0, v[148:149]
	global_store_dwordx4 v[124:125], v[120:123], off
	v_pk_mul_f32 v[116:117], v[116:117], v[200:201] op_sel_hi:[1,0]
	v_pk_mul_f32 v[118:119], v[118:119], v[200:201] op_sel_hi:[1,0]
	v_pk_mul_f32 v[120:121], v[114:115], v[200:201] op_sel_hi:[1,0]
	v_pk_mul_f32 v[114:115], v[112:113], v[200:201] op_sel_hi:[1,0]
	v_lshlrev_b32_e32 v112, 16, v170
	v_and_b32_e32 v113, 0xffff0000, v170
	v_mul_f32_e32 v112, v116, v112
	v_mul_f32_e32 v113, v117, v113
	v_cvt_pk_bf16_f32 v112, v112, v113
	v_lshlrev_b32_e32 v113, 16, v171
	v_and_b32_e32 v116, 0xffff0000, v171
	v_mul_f32_e32 v113, v118, v113
	v_mul_f32_e32 v116, v119, v116
	v_cvt_pk_bf16_f32 v113, v113, v116
	v_lshlrev_b32_e32 v116, 16, v172
	v_mul_f32_e32 v114, v114, v116
	v_and_b32_e32 v116, 0xffff0000, v172
	v_mul_f32_e32 v115, v115, v116
	v_cvt_pk_bf16_f32 v114, v114, v115
	v_lshlrev_b32_e32 v115, 16, v173
	v_mul_f32_e32 v115, v120, v115
	v_and_b32_e32 v116, 0xffff0000, v173
	v_mul_f32_e32 v116, v121, v116
	v_cvt_pk_bf16_f32 v115, v115, v116
	global_store_dwordx4 v[124:125], v[112:115], off offset:256
	v_pk_mul_f32 v[108:109], v[108:109], v[202:203] op_sel_hi:[1,0]
	v_pk_mul_f32 v[110:111], v[110:111], v[202:203] op_sel_hi:[1,0]
	v_pk_mul_f32 v[112:113], v[106:107], v[202:203] op_sel_hi:[1,0]
	v_pk_mul_f32 v[106:107], v[104:105], v[202:203] op_sel_hi:[1,0]
	v_lshlrev_b32_e32 v104, 16, v174
	v_and_b32_e32 v105, 0xffff0000, v174
	v_mul_f32_e32 v104, v108, v104
	v_mul_f32_e32 v105, v109, v105
	v_cvt_pk_bf16_f32 v104, v104, v105
	v_lshlrev_b32_e32 v105, 16, v175
	v_and_b32_e32 v108, 0xffff0000, v175
	v_mul_f32_e32 v105, v110, v105
	v_mul_f32_e32 v108, v111, v108
	v_cvt_pk_bf16_f32 v105, v105, v108
	v_lshlrev_b32_e32 v108, 16, v176
	v_mul_f32_e32 v106, v106, v108
	v_and_b32_e32 v108, 0xffff0000, v176
	v_mul_f32_e32 v107, v107, v108
	v_cvt_pk_bf16_f32 v106, v106, v107
	v_lshlrev_b32_e32 v107, 16, v177
	v_and_b32_e32 v108, 0xffff0000, v177
	v_mul_f32_e32 v107, v112, v107
	v_mul_f32_e32 v108, v113, v108
	v_cvt_pk_bf16_f32 v107, v107, v108
	v_lshl_add_u64 v[108:109], s[26:27], 0, v[186:187]
	v_lshl_add_u64 v[108:109], v[108:109], 0, v[148:149]
	global_store_dwordx4 v[108:109], v[104:107], off
	v_pk_mul_f32 v[100:101], v[100:101], v[202:203] op_sel_hi:[1,0]
	v_pk_mul_f32 v[102:103], v[102:103], v[202:203] op_sel_hi:[1,0]
	v_pk_mul_f32 v[104:105], v[98:99], v[202:203] op_sel_hi:[1,0]
	v_pk_mul_f32 v[98:99], v[96:97], v[202:203] op_sel_hi:[1,0]
	v_lshlrev_b32_e32 v96, 16, v178
	v_and_b32_e32 v97, 0xffff0000, v178
	v_mul_f32_e32 v96, v100, v96
	v_mul_f32_e32 v97, v101, v97
	v_cvt_pk_bf16_f32 v96, v96, v97
	v_lshlrev_b32_e32 v97, 16, v179
	v_and_b32_e32 v100, 0xffff0000, v179
	v_mul_f32_e32 v97, v102, v97
	v_mul_f32_e32 v100, v103, v100
	v_cvt_pk_bf16_f32 v97, v97, v100
	v_lshlrev_b32_e32 v100, 16, v180
	v_mul_f32_e32 v98, v98, v100
	v_and_b32_e32 v100, 0xffff0000, v180
	v_mul_f32_e32 v99, v99, v100
	v_cvt_pk_bf16_f32 v98, v98, v99
	v_lshlrev_b32_e32 v99, 16, v181
	v_mul_f32_e32 v99, v104, v99
	v_and_b32_e32 v100, 0xffff0000, v181
	v_mul_f32_e32 v100, v105, v100
	v_cvt_pk_bf16_f32 v99, v99, v100
	global_store_dwordx4 v[108:109], v[96:99], off offset:256
	v_pk_mul_f32 v[92:93], v[92:93], v[204:205] op_sel_hi:[1,0]
	v_pk_mul_f32 v[94:95], v[94:95], v[204:205] op_sel_hi:[1,0]
	v_pk_mul_f32 v[96:97], v[90:91], v[204:205] op_sel_hi:[1,0]
	v_pk_mul_f32 v[90:91], v[88:89], v[204:205] op_sel_hi:[1,0]
	v_lshlrev_b32_e32 v88, 16, v182
	v_and_b32_e32 v89, 0xffff0000, v182
	v_mul_f32_e32 v88, v92, v88
	v_mul_f32_e32 v89, v93, v89
	v_cvt_pk_bf16_f32 v88, v88, v89
	v_lshlrev_b32_e32 v89, 16, v183
	v_and_b32_e32 v92, 0xffff0000, v183
	v_mul_f32_e32 v89, v94, v89
	v_mul_f32_e32 v92, v95, v92
	v_cvt_pk_bf16_f32 v89, v89, v92
	v_lshlrev_b32_e32 v92, 16, v184
	v_mul_f32_e32 v90, v90, v92
	v_and_b32_e32 v92, 0xffff0000, v184
	v_mul_f32_e32 v91, v91, v92
	v_cvt_pk_bf16_f32 v90, v90, v91
	v_lshlrev_b32_e32 v91, 16, v185
	v_and_b32_e32 v92, 0xffff0000, v185
	v_mul_f32_e32 v91, v96, v91
	v_mul_f32_e32 v92, v97, v92
	v_cvt_pk_bf16_f32 v91, v91, v92
	v_lshl_add_u64 v[92:93], s[26:27], 0, v[198:199]
	v_lshl_add_u64 v[92:93], v[92:93], 0, v[148:149]
	global_store_dwordx4 v[92:93], v[88:91], off
	v_pk_mul_f32 v[84:85], v[84:85], v[204:205] op_sel_hi:[1,0]
	v_pk_mul_f32 v[86:87], v[86:87], v[204:205] op_sel_hi:[1,0]
	v_pk_mul_f32 v[88:89], v[82:83], v[204:205] op_sel_hi:[1,0]
	v_pk_mul_f32 v[82:83], v[80:81], v[204:205] op_sel_hi:[1,0]
	v_lshlrev_b32_e32 v80, 16, v190
	v_and_b32_e32 v81, 0xffff0000, v190
	v_mul_f32_e32 v80, v84, v80
	v_mul_f32_e32 v81, v85, v81
	v_cvt_pk_bf16_f32 v80, v80, v81
	v_lshlrev_b32_e32 v81, 16, v191
	v_and_b32_e32 v84, 0xffff0000, v191
	v_mul_f32_e32 v81, v86, v81
	v_mul_f32_e32 v84, v87, v84
	v_cvt_pk_bf16_f32 v81, v81, v84
	v_lshlrev_b32_e32 v84, 16, v192
	v_mul_f32_e32 v82, v82, v84
	v_and_b32_e32 v84, 0xffff0000, v192
	v_mul_f32_e32 v83, v83, v84
	v_cvt_pk_bf16_f32 v82, v82, v83
	v_lshlrev_b32_e32 v83, 16, v193
	v_mul_f32_e32 v83, v88, v83
	v_and_b32_e32 v84, 0xffff0000, v193
	v_mul_f32_e32 v84, v89, v84
	v_cvt_pk_bf16_f32 v83, v83, v84
	global_store_dwordx4 v[92:93], v[80:83], off offset:256
	v_pk_mul_f32 v[76:77], v[76:77], v[158:159] op_sel_hi:[1,0]
	v_pk_mul_f32 v[78:79], v[78:79], v[158:159] op_sel_hi:[1,0]
	v_pk_mul_f32 v[80:81], v[74:75], v[158:159] op_sel_hi:[1,0]
	v_pk_mul_f32 v[74:75], v[72:73], v[158:159] op_sel_hi:[1,0]
	v_lshlrev_b32_e32 v72, 16, v194
	v_and_b32_e32 v73, 0xffff0000, v194
	v_mul_f32_e32 v72, v76, v72
	v_mul_f32_e32 v73, v77, v73
	v_cvt_pk_bf16_f32 v72, v72, v73
	v_lshlrev_b32_e32 v73, 16, v195
	v_and_b32_e32 v76, 0xffff0000, v195
	v_mul_f32_e32 v73, v78, v73
	v_mul_f32_e32 v76, v79, v76
	v_cvt_pk_bf16_f32 v73, v73, v76
	v_lshlrev_b32_e32 v76, 16, v196
	v_mul_f32_e32 v74, v74, v76
	v_and_b32_e32 v76, 0xffff0000, v196
	v_mul_f32_e32 v75, v75, v76
	v_cvt_pk_bf16_f32 v74, v74, v75
	v_lshlrev_b32_e32 v75, 16, v197
	v_and_b32_e32 v76, 0xffff0000, v197
	v_mul_f32_e32 v75, v80, v75
	v_mul_f32_e32 v76, v81, v76
	v_cvt_pk_bf16_f32 v75, v75, v76
	v_lshl_add_u64 v[76:77], s[26:27], 0, v[156:157]
	v_lshl_add_u64 v[76:77], v[76:77], 0, v[148:149]
	global_store_dwordx4 v[76:77], v[72:75], off
	v_pk_mul_f32 v[68:69], v[68:69], v[158:159] op_sel_hi:[1,0]
	v_pk_mul_f32 v[70:71], v[70:71], v[158:159] op_sel_hi:[1,0]
	v_pk_mul_f32 v[72:73], v[66:67], v[158:159] op_sel_hi:[1,0]
	v_pk_mul_f32 v[66:67], v[64:65], v[158:159] op_sel_hi:[1,0]
	v_lshlrev_b32_e32 v64, 16, v128
	v_and_b32_e32 v65, 0xffff0000, v128
	v_mul_f32_e32 v64, v68, v64
	v_mul_f32_e32 v65, v69, v65
	v_cvt_pk_bf16_f32 v64, v64, v65
	v_lshlrev_b32_e32 v65, 16, v129
	v_and_b32_e32 v68, 0xffff0000, v129
	v_mul_f32_e32 v65, v70, v65
	v_mul_f32_e32 v68, v71, v68
	v_cvt_pk_bf16_f32 v65, v65, v68
	v_lshlrev_b32_e32 v68, 16, v130
	v_mul_f32_e32 v66, v66, v68
	v_and_b32_e32 v68, 0xffff0000, v130
	v_mul_f32_e32 v67, v67, v68
	v_cvt_pk_bf16_f32 v66, v66, v67
	v_lshlrev_b32_e32 v67, 16, v131
	v_mul_f32_e32 v67, v72, v67
	v_and_b32_e32 v68, 0xffff0000, v131
	v_mul_f32_e32 v68, v73, v68
	v_cvt_pk_bf16_f32 v67, v67, v68
	v_lshl_add_u64 v[100:101], v[154:155], 0, s[6:7]
	v_lshl_add_u64 v[102:103], v[154:155], 0, s[12:13]
	v_lshl_add_u64 v[104:105], v[154:155], 0, s[14:15]
	global_store_dwordx4 v[76:77], v[64:67], off offset:256
	v_lshl_add_u64 v[92:93], v[150:151], 0, v[104:105]
	v_lshl_add_u64 v[70:71], v[154:155], 0, s[18:19]
	v_lshl_add_u64 v[64:65], v[150:151], 0, v[100:101]
	v_lshl_add_u64 v[66:67], v[150:151], 0, v[102:103]
	v_lshl_add_u64 v[112:113], v[150:151], 0, v[70:71]
	s_nop 0
	s_nop 0
	global_load_dwordx4 v[96:99], v[112:113], off
	global_load_dwordx4 v[64:67], v[112:113], off offset:256
	s_waitcnt vmcnt(10)
	v_pk_mul_f32 v[60:61], v[60:61], v[216:217] op_sel_hi:[1,0]
	v_pk_mul_f32 v[112:113], v[58:59], v[216:217] op_sel_hi:[1,0]
	v_pk_mul_f32 v[58:59], v[56:57], v[216:217] op_sel_hi:[1,0]
	v_lshlrev_b32_e32 v56, 16, v236
	v_and_b32_e32 v57, 0xffff0000, v236
	v_mul_f32_e32 v56, v60, v56
	v_mul_f32_e32 v57, v61, v57
	v_pk_mul_f32 v[62:63], v[62:63], v[216:217] op_sel_hi:[1,0]
	v_cvt_pk_bf16_f32 v56, v56, v57
	v_lshlrev_b32_e32 v57, 16, v237
	v_and_b32_e32 v60, 0xffff0000, v237
	v_mul_f32_e32 v57, v62, v57
	v_mul_f32_e32 v60, v63, v60
	v_cvt_pk_bf16_f32 v57, v57, v60
	v_lshlrev_b32_e32 v60, 16, v238
	v_mul_f32_e32 v58, v58, v60
	v_and_b32_e32 v60, 0xffff0000, v238
	v_mul_f32_e32 v59, v59, v60
	v_cvt_pk_bf16_f32 v58, v58, v59
	v_lshlrev_b32_e32 v59, 16, v239
	v_and_b32_e32 v60, 0xffff0000, v239
	v_mul_f32_e32 v59, v112, v59
	v_mul_f32_e32 v60, v113, v60
	v_cvt_pk_bf16_f32 v59, v59, v60
	v_lshl_add_u64 v[60:61], s[26:27], 0, v[100:101]
	v_lshl_add_u64 v[60:61], v[60:61], 0, v[148:149]
	global_store_dwordx4 v[60:61], v[56:59], off
	v_pk_mul_f32 v[52:53], v[52:53], v[216:217] op_sel_hi:[1,0]
	v_pk_mul_f32 v[54:55], v[54:55], v[216:217] op_sel_hi:[1,0]
	v_pk_mul_f32 v[56:57], v[50:51], v[216:217] op_sel_hi:[1,0]
	v_pk_mul_f32 v[50:51], v[48:49], v[216:217] op_sel_hi:[1,0]
	v_lshlrev_b32_e32 v48, 16, v240
	v_and_b32_e32 v49, 0xffff0000, v240
	v_mul_f32_e32 v48, v52, v48
	v_mul_f32_e32 v49, v53, v49
	v_cvt_pk_bf16_f32 v48, v48, v49
	v_lshlrev_b32_e32 v49, 16, v241
	v_and_b32_e32 v52, 0xffff0000, v241
	v_mul_f32_e32 v49, v54, v49
	v_mul_f32_e32 v52, v55, v52
	v_cvt_pk_bf16_f32 v49, v49, v52
	v_lshlrev_b32_e32 v52, 16, v242
	v_mul_f32_e32 v50, v50, v52
	v_and_b32_e32 v52, 0xffff0000, v242
	v_mul_f32_e32 v51, v51, v52
	v_cvt_pk_bf16_f32 v50, v50, v51
	v_lshlrev_b32_e32 v51, 16, v243
	v_mul_f32_e32 v51, v56, v51
	v_and_b32_e32 v52, 0xffff0000, v243
	v_mul_f32_e32 v52, v57, v52
	v_cvt_pk_bf16_f32 v51, v51, v52
	global_store_dwordx4 v[60:61], v[48:51], off offset:256
	v_pk_mul_f32 v[44:45], v[44:45], v[218:219] op_sel_hi:[1,0]
	v_pk_mul_f32 v[46:47], v[46:47], v[218:219] op_sel_hi:[1,0]
	v_pk_mul_f32 v[48:49], v[42:43], v[218:219] op_sel_hi:[1,0]
	v_pk_mul_f32 v[42:43], v[40:41], v[218:219] op_sel_hi:[1,0]
	v_lshlrev_b32_e32 v40, 16, v244
	v_and_b32_e32 v41, 0xffff0000, v244
	v_mul_f32_e32 v40, v44, v40
	v_mul_f32_e32 v41, v45, v41
	v_cvt_pk_bf16_f32 v40, v40, v41
	v_lshlrev_b32_e32 v41, 16, v245
	v_and_b32_e32 v44, 0xffff0000, v245
	v_mul_f32_e32 v41, v46, v41
	v_mul_f32_e32 v44, v47, v44
	v_cvt_pk_bf16_f32 v41, v41, v44
	v_lshlrev_b32_e32 v44, 16, v246
	v_mul_f32_e32 v42, v42, v44
	v_and_b32_e32 v44, 0xffff0000, v246
	v_mul_f32_e32 v43, v43, v44
	v_cvt_pk_bf16_f32 v42, v42, v43
	v_lshlrev_b32_e32 v43, 16, v247
	v_and_b32_e32 v44, 0xffff0000, v247
	v_mul_f32_e32 v43, v48, v43
	v_mul_f32_e32 v44, v49, v44
	v_cvt_pk_bf16_f32 v43, v43, v44
	v_lshl_add_u64 v[44:45], s[26:27], 0, v[102:103]
	v_lshl_add_u64 v[44:45], v[44:45], 0, v[148:149]
	global_store_dwordx4 v[44:45], v[40:43], off
	v_pk_mul_f32 v[36:37], v[36:37], v[218:219] op_sel_hi:[1,0]
	v_pk_mul_f32 v[38:39], v[38:39], v[218:219] op_sel_hi:[1,0]
	v_pk_mul_f32 v[40:41], v[34:35], v[218:219] op_sel_hi:[1,0]
	v_pk_mul_f32 v[34:35], v[32:33], v[218:219] op_sel_hi:[1,0]
	v_lshlrev_b32_e32 v32, 16, v248
	v_and_b32_e32 v33, 0xffff0000, v248
	v_mul_f32_e32 v32, v36, v32
	v_mul_f32_e32 v33, v37, v33
	v_cvt_pk_bf16_f32 v32, v32, v33
	v_lshlrev_b32_e32 v33, 16, v249
	v_and_b32_e32 v36, 0xffff0000, v249
	v_mul_f32_e32 v33, v38, v33
	v_mul_f32_e32 v36, v39, v36
	v_cvt_pk_bf16_f32 v33, v33, v36
	v_lshlrev_b32_e32 v36, 16, v250
	v_mul_f32_e32 v34, v34, v36
	v_and_b32_e32 v36, 0xffff0000, v250
	v_mul_f32_e32 v35, v35, v36
	v_cvt_pk_bf16_f32 v34, v34, v35
	v_lshlrev_b32_e32 v35, 16, v251
	v_mul_f32_e32 v35, v40, v35
	v_and_b32_e32 v36, 0xffff0000, v251
	v_mul_f32_e32 v36, v41, v36
	v_cvt_pk_bf16_f32 v35, v35, v36
	global_store_dwordx4 v[44:45], v[32:35], off offset:256
	v_pk_mul_f32 v[28:29], v[28:29], v[220:221] op_sel_hi:[1,0]
	v_pk_mul_f32 v[30:31], v[30:31], v[220:221] op_sel_hi:[1,0]
	v_pk_mul_f32 v[32:33], v[26:27], v[220:221] op_sel_hi:[1,0]
	v_pk_mul_f32 v[26:27], v[24:25], v[220:221] op_sel_hi:[1,0]
	v_lshlrev_b32_e32 v24, 16, v208
	v_and_b32_e32 v25, 0xffff0000, v208
	v_mul_f32_e32 v24, v28, v24
	v_mul_f32_e32 v25, v29, v25
	v_cvt_pk_bf16_f32 v24, v24, v25
	v_lshlrev_b32_e32 v25, 16, v209
	v_and_b32_e32 v28, 0xffff0000, v209
	v_mul_f32_e32 v25, v30, v25
	v_mul_f32_e32 v28, v31, v28
	v_cvt_pk_bf16_f32 v25, v25, v28
	v_lshlrev_b32_e32 v28, 16, v210
	v_mul_f32_e32 v26, v26, v28
	v_and_b32_e32 v28, 0xffff0000, v210
	v_mul_f32_e32 v27, v27, v28
	v_cvt_pk_bf16_f32 v26, v26, v27
	v_lshlrev_b32_e32 v27, 16, v211
	v_and_b32_e32 v28, 0xffff0000, v211
	v_mul_f32_e32 v27, v32, v27
	v_mul_f32_e32 v28, v33, v28
	v_cvt_pk_bf16_f32 v27, v27, v28
	v_lshl_add_u64 v[28:29], s[26:27], 0, v[104:105]
	v_lshl_add_u64 v[28:29], v[28:29], 0, v[148:149]
	global_store_dwordx4 v[28:29], v[24:27], off
	v_pk_mul_f32 v[20:21], v[20:21], v[220:221] op_sel_hi:[1,0]
	v_pk_mul_f32 v[22:23], v[22:23], v[220:221] op_sel_hi:[1,0]
	v_pk_mul_f32 v[24:25], v[18:19], v[220:221] op_sel_hi:[1,0]
	v_pk_mul_f32 v[18:19], v[16:17], v[220:221] op_sel_hi:[1,0]
	v_lshlrev_b32_e32 v16, 16, v212
	v_and_b32_e32 v17, 0xffff0000, v212
	v_mul_f32_e32 v16, v20, v16
	v_mul_f32_e32 v17, v21, v17
	v_cvt_pk_bf16_f32 v16, v16, v17
	v_lshlrev_b32_e32 v17, 16, v213
	v_and_b32_e32 v20, 0xffff0000, v213
	v_mul_f32_e32 v17, v22, v17
	v_mul_f32_e32 v20, v23, v20
	v_cvt_pk_bf16_f32 v17, v17, v20
	v_lshlrev_b32_e32 v20, 16, v214
	v_mul_f32_e32 v18, v18, v20
	v_and_b32_e32 v20, 0xffff0000, v214
	v_mul_f32_e32 v19, v19, v20
	v_cvt_pk_bf16_f32 v18, v18, v19
	v_lshlrev_b32_e32 v19, 16, v215
	v_mul_f32_e32 v19, v24, v19
	v_and_b32_e32 v20, 0xffff0000, v215
	v_mul_f32_e32 v20, v25, v20
	v_cvt_pk_bf16_f32 v19, v19, v20
	global_store_dwordx4 v[28:29], v[16:19], off offset:256
	s_waitcnt vmcnt(6)
	v_pk_mul_f32 v[12:13], v[12:13], v[252:253] op_sel_hi:[1,0]
	v_pk_mul_f32 v[14:15], v[14:15], v[252:253] op_sel_hi:[1,0]
	v_pk_mul_f32 v[16:17], v[10:11], v[252:253] op_sel_hi:[1,0]
	v_pk_mul_f32 v[10:11], v[8:9], v[252:253] op_sel_hi:[1,0]
	v_lshlrev_b32_e32 v8, 16, v96
	v_and_b32_e32 v9, 0xffff0000, v96
	v_mul_f32_e32 v8, v12, v8
	v_mul_f32_e32 v9, v13, v9
	v_cvt_pk_bf16_f32 v8, v8, v9
	v_lshlrev_b32_e32 v9, 16, v97
	v_and_b32_e32 v12, 0xffff0000, v97
	v_mul_f32_e32 v9, v14, v9
	v_mul_f32_e32 v12, v15, v12
	v_cvt_pk_bf16_f32 v9, v9, v12
	v_lshlrev_b32_e32 v12, 16, v98
	v_mul_f32_e32 v10, v10, v12
	v_and_b32_e32 v12, 0xffff0000, v98
	v_mul_f32_e32 v11, v11, v12
	v_cvt_pk_bf16_f32 v10, v10, v11
	v_lshlrev_b32_e32 v11, 16, v99
	v_and_b32_e32 v12, 0xffff0000, v99
	v_mul_f32_e32 v11, v16, v11
	v_mul_f32_e32 v12, v17, v12
	v_cvt_pk_bf16_f32 v11, v11, v12
	v_lshl_add_u64 v[12:13], s[26:27], 0, v[70:71]
	v_lshl_add_u64 v[12:13], v[12:13], 0, v[148:149]
	global_store_dwordx4 v[12:13], v[8:11], off
	v_pk_mul_f32 v[4:5], v[4:5], v[252:253] op_sel_hi:[1,0]
	v_pk_mul_f32 v[6:7], v[6:7], v[252:253] op_sel_hi:[1,0]
	v_pk_mul_f32 v[8:9], v[2:3], v[252:253] op_sel_hi:[1,0]
	v_pk_mul_f32 v[2:3], v[0:1], v[252:253] op_sel_hi:[1,0]
	v_lshlrev_b32_e32 v0, 16, v64
	v_and_b32_e32 v1, 0xffff0000, v64
	v_mul_f32_e32 v0, v4, v0
	v_mul_f32_e32 v1, v5, v1
	v_cvt_pk_bf16_f32 v0, v0, v1
	v_lshlrev_b32_e32 v1, 16, v65
	v_and_b32_e32 v4, 0xffff0000, v65
	v_mul_f32_e32 v1, v6, v1
	v_mul_f32_e32 v4, v7, v4
	v_cvt_pk_bf16_f32 v1, v1, v4
	v_lshlrev_b32_e32 v4, 16, v66
	v_mul_f32_e32 v2, v2, v4
	v_and_b32_e32 v4, 0xffff0000, v66
	v_mul_f32_e32 v3, v3, v4
	v_cvt_pk_bf16_f32 v2, v2, v3
	v_lshlrev_b32_e32 v3, 16, v67
	v_mul_f32_e32 v3, v8, v3
	v_and_b32_e32 v4, 0xffff0000, v67
	s_and_b64 vcc, exec, s[2:3]
	s_mov_b32 s54, s20
	s_mov_b32 s30, s22
	s_mov_b64 s[36:37], s[28:29]
	s_mov_b64 s[34:35], s[24:25]
	v_mul_f32_e32 v4, v9, v4
	v_cvt_pk_bf16_f32 v3, v3, v4
	global_store_dwordx4 v[12:13], v[0:3], off offset:256
	s_cbranch_vccz .LBB0_279
	s_waitcnt vmcnt(0)
	s_cmpk_gt_u32 s40, 0xff
	s_cbranch_scc1 .LBB0_290
	s_barrier
